# grid barrier: the XCD leaders no longer wait for their bookkeeping atomics (generation words nobody polls) before rejoining their workgroup
# baseline (speedup 1.0000x reference)
; __device__ __forceinline__ unsigned xb_ld(unsigned* p)              { return __hip_atomic_load(p, __ATOMIC_RELAXED, __HIP_MEMORY_SCOPE_AGENT); }
; __device__ __forceinline__ unsigned xb_add(unsigned* p, unsigned v) { return __hip_atomic_fetch_add(p, v, __ATOMIC_RELAXED, __HIP_MEMORY_SCOPE_AGENT); }
; #define XB_SPIN(cond, bar) do { unsigned _sp = 0; while (cond) { __builtin_amdgcn_s_sleep(1); \
;     if ((++_sp & 255u) == 0u) { if (xb_ld(&(bar)[XB_TMO])) break; if (_sp > XB_SPIN_CAP) { atomicAdd(&(bar)[XB_TMO], 1u); break; } } } } while (0)
; __device__ __forceinline__ void xcd_barrier(const XcdBarrier& b) {
;     ...
;             if (og + 1u == (tg + 1u) * nx) xb_add(&bar[XB_TOPGEN], 1u);
;             else XB_SPIN(xb_ld(&bar[XB_TOPGEN]) == tg, bar);
;             __builtin_amdgcn_fence(__ATOMIC_ACQUIRE, "agent");
;             xb_add(&bar[XB_XGEN(b.x)], 1u);
;             asm volatile("s_waitcnt vmcnt(0)" ::: "memory");
.LBB0_103:
	s_or_b64 exec, exec, s[2:3]
	s_mov_b64 s[2:3], exec
	v_mbcnt_lo_u32_b32 v0, s2, 0
	v_mbcnt_hi_u32_b32 v0, s3, v0
	v_cmp_eq_u32_e32 vcc, 0, v0
	s_and_saveexec_b64 s[4:5], vcc
	s_cbranch_execz .LBB0_105
	s_bcnt1_i32_b64 s2, s[2:3]
	v_mov_b32_e32 v1, s2
	v_readlane_b32 s2, v252, 62
	v_mov_b32_e32 v0, 0
	v_readlane_b32 s3, v252, 63
	s_nop 4
	global_atomic_add v0, v1, s[2:3]
.LBB0_105:
	s_or_b64 exec, exec, s[4:5]
.LBB0_106:
	s_or_b64 exec, exec, s[0:1]

; __device__ __forceinline__ unsigned xb_add(unsigned* p, unsigned v) { return __hip_atomic_fetch_add(p, v, __ATOMIC_RELAXED, __HIP_MEMORY_SCOPE_AGENT); }
; __device__ __forceinline__ void xcd_barrier(const XcdBarrier& b) {
;     ...
;             xb_add(&bar[XB_XGEN(b.x)], 1u);
;             asm volatile("s_waitcnt vmcnt(0)" ::: "memory");
.LBB0_108:
	s_or_b64 exec, exec, s[24:25]
.LBB0_109:
	s_or_b64 exec, exec, s[2:3]

; __device__ __forceinline__ unsigned xb_ld(unsigned* p)              { return __hip_atomic_load(p, __ATOMIC_RELAXED, __HIP_MEMORY_SCOPE_AGENT); }
; __device__ __forceinline__ unsigned xb_add(unsigned* p, unsigned v) { return __hip_atomic_fetch_add(p, v, __ATOMIC_RELAXED, __HIP_MEMORY_SCOPE_AGENT); }
; #define XB_SPIN(cond, bar) do { unsigned _sp = 0; while (cond) { __builtin_amdgcn_s_sleep(1); \
;     if ((++_sp & 255u) == 0u) { if (xb_ld(&(bar)[XB_TMO])) break; if (_sp > XB_SPIN_CAP) { atomicAdd(&(bar)[XB_TMO], 1u); break; } } } } while (0)
; __device__ __forceinline__ void xcd_barrier(const XcdBarrier& b) {
;     ...
;             if (og + 1u == (tg + 1u) * nx) xb_add(&bar[XB_TOPGEN], 1u);
;             else XB_SPIN(xb_ld(&bar[XB_TOPGEN]) == tg, bar);
;             __builtin_amdgcn_fence(__ATOMIC_ACQUIRE, "agent");
;             xb_add(&bar[XB_XGEN(b.x)], 1u);
;             asm volatile("s_waitcnt vmcnt(0)" ::: "memory");
.LBB0_273:
	s_or_b64 exec, exec, s[12:13]
	s_mov_b64 s[12:13], exec
	v_mbcnt_lo_u32_b32 v0, s12, 0
	v_mbcnt_hi_u32_b32 v0, s13, v0
	v_cmp_eq_u32_e32 vcc, 0, v0
	s_and_saveexec_b64 s[24:25], vcc
	s_cbranch_execz .LBB0_275
	s_bcnt1_i32_b64 s0, s[12:13]
	v_readlane_b32 s12, v252, 62
	v_mov_b32_e32 v0, s0
	v_readlane_b32 s13, v252, 63
	s_nop 4
	global_atomic_add v185, v0, s[12:13]
.LBB0_275:
	s_or_b64 exec, exec, s[24:25]
.LBB0_276:
	s_or_b64 exec, exec, s[2:3]

; __device__ __forceinline__ unsigned xb_add(unsigned* p, unsigned v) { return __hip_atomic_fetch_add(p, v, __ATOMIC_RELAXED, __HIP_MEMORY_SCOPE_AGENT); }
; __device__ __forceinline__ void xcd_barrier(const XcdBarrier& b) {
;     ...
;             xb_add(&bar[XB_XGEN(b.x)], 1u);
;             asm volatile("s_waitcnt vmcnt(0)" ::: "memory");
.LBB0_746:
	s_or_b64 exec, exec, s[24:25]
.LBB0_747:
	s_or_b64 exec, exec, s[2:3]

; __device__ __forceinline__ unsigned xb_add(unsigned* p, unsigned v) { return __hip_atomic_fetch_add(p, v, __ATOMIC_RELAXED, __HIP_MEMORY_SCOPE_AGENT); }
; __device__ __forceinline__ void xcd_barrier(const XcdBarrier& b) {
;     ...
;             xb_add(&bar[XB_XGEN(b.x)], 1u);
;             asm volatile("s_waitcnt vmcnt(0)" ::: "memory");
.LBB0_805:
	s_or_b64 exec, exec, s[24:25]
.LBB0_806:
	s_or_b64 exec, exec, s[2:3]

; __device__ __forceinline__ unsigned xb_add(unsigned* p, unsigned v) { return __hip_atomic_fetch_add(p, v, __ATOMIC_RELAXED, __HIP_MEMORY_SCOPE_AGENT); }
; __device__ __forceinline__ void xcd_barrier(const XcdBarrier& b) {
;     ...
;             xb_add(&bar[XB_XGEN(b.x)], 1u);
;             asm volatile("s_waitcnt vmcnt(0)" ::: "memory");
.LBB0_884:
	s_or_b64 exec, exec, s[24:25]
.LBB0_885:
	s_or_b64 exec, exec, s[2:3]

; __device__ __forceinline__ unsigned xb_add(unsigned* p, unsigned v) { return __hip_atomic_fetch_add(p, v, __ATOMIC_RELAXED, __HIP_MEMORY_SCOPE_AGENT); }
; __device__ __forceinline__ void xcd_barrier(const XcdBarrier& b) {
;     ...
;             xb_add(&bar[XB_XGEN(b.x)], 1u);
;             asm volatile("s_waitcnt vmcnt(0)" ::: "memory");
.LBB0_960:
	s_or_b64 exec, exec, s[24:25]
.LBB0_961:
	s_or_b64 exec, exec, s[2:3]

; __device__ __forceinline__ unsigned xb_add(unsigned* p, unsigned v) { return __hip_atomic_fetch_add(p, v, __ATOMIC_RELAXED, __HIP_MEMORY_SCOPE_AGENT); }
; __device__ __forceinline__ void xcd_barrier(const XcdBarrier& b) {
;     ...
;             xb_add(&bar[XB_XGEN(b.x)], 1u);
;             asm volatile("s_waitcnt vmcnt(0)" ::: "memory");
.LBB0_1312:
	s_or_b64 exec, exec, s[24:25]
.LBB0_1313:
	s_or_b64 exec, exec, s[2:3]

; __device__ __forceinline__ unsigned xb_add(unsigned* p, unsigned v) { return __hip_atomic_fetch_add(p, v, __ATOMIC_RELAXED, __HIP_MEMORY_SCOPE_AGENT); }
; __device__ __forceinline__ void xcd_barrier(const XcdBarrier& b) {
;     ...
;             xb_add(&bar[XB_XGEN(b.x)], 1u);
;             asm volatile("s_waitcnt vmcnt(0)" ::: "memory");
.LBB0_1425:
	s_or_b64 exec, exec, s[24:25]
.LBB0_1426:
	s_or_b64 exec, exec, s[2:3]

; __device__ __forceinline__ unsigned xb_add(unsigned* p, unsigned v) { return __hip_atomic_fetch_add(p, v, __ATOMIC_RELAXED, __HIP_MEMORY_SCOPE_AGENT); }
; __device__ __forceinline__ void xcd_barrier(const XcdBarrier& b) {
;     ...
;             xb_add(&bar[XB_XGEN(b.x)], 1u);
;             asm volatile("s_waitcnt vmcnt(0)" ::: "memory");
.LBB0_1496:
	s_or_b64 exec, exec, s[24:25]
.LBB0_1497:
	s_or_b64 exec, exec, s[2:3]

; __device__ __forceinline__ unsigned xb_add(unsigned* p, unsigned v) { return __hip_atomic_fetch_add(p, v, __ATOMIC_RELAXED, __HIP_MEMORY_SCOPE_AGENT); }
; __device__ __forceinline__ void xcd_barrier(const XcdBarrier& b) {
;     ...
;             xb_add(&bar[XB_XGEN(b.x)], 1u);
;             asm volatile("s_waitcnt vmcnt(0)" ::: "memory");
.LBB0_1558:
	s_or_b64 exec, exec, s[24:25]
.LBB0_1559:
	s_or_b64 exec, exec, s[2:3]

; __device__ __forceinline__ unsigned xb_add(unsigned* p, unsigned v) { return __hip_atomic_fetch_add(p, v, __ATOMIC_RELAXED, __HIP_MEMORY_SCOPE_AGENT); }
; __device__ __forceinline__ void xcd_barrier(const XcdBarrier& b) {
;     ...
;             xb_add(&bar[XB_XGEN(b.x)], 1u);
;             asm volatile("s_waitcnt vmcnt(0)" ::: "memory");
.LBB0_1637:
	s_or_b64 exec, exec, s[24:25]
.LBB0_1638:
	s_or_b64 exec, exec, s[2:3]

; __device__ __forceinline__ unsigned xb_ld(unsigned* p)              { return __hip_atomic_load(p, __ATOMIC_RELAXED, __HIP_MEMORY_SCOPE_AGENT); }
; __device__ __forceinline__ unsigned xb_add(unsigned* p, unsigned v) { return __hip_atomic_fetch_add(p, v, __ATOMIC_RELAXED, __HIP_MEMORY_SCOPE_AGENT); }
; #define XB_SPIN(cond, bar) do { unsigned _sp = 0; while (cond) { __builtin_amdgcn_s_sleep(1); \
;     if ((++_sp & 255u) == 0u) { if (xb_ld(&(bar)[XB_TMO])) break; if (_sp > XB_SPIN_CAP) { atomicAdd(&(bar)[XB_TMO], 1u); break; } } } } while (0)
; __device__ __forceinline__ void xcd_barrier(const XcdBarrier& b) {
;     ...
;             if (og + 1u == (tg + 1u) * nx) xb_add(&bar[XB_TOPGEN], 1u);
;             else XB_SPIN(xb_ld(&bar[XB_TOPGEN]) == tg, bar);
;             __builtin_amdgcn_fence(__ATOMIC_ACQUIRE, "agent");
;             xb_add(&bar[XB_XGEN(b.x)], 1u);
.LBB0_1697:
	s_or_b64 exec, exec, s[12:13]
	s_mov_b64 s[12:13], exec
	v_mbcnt_lo_u32_b32 v0, s12, 0
	v_mbcnt_hi_u32_b32 v0, s13, v0
	v_cmp_eq_u32_e32 vcc, 0, v0
	s_and_saveexec_b64 s[24:25], vcc
	s_cbranch_execnz .LBB0_1698
	s_getpc_b64 s[98:99]
